# POST elementwise loops with more memory-level parallelism: gated-norm loop unrolled by two with all four data loads up front (renamed registers) and invariant norm-weight loads hoisted; LSE-merge loop
# speedup vs baseline: 1.0063x; 1.0063x over previous
.LBB0_761:
	v_ashrrev_i32_e32 v12, 7, v1
	v_ashrrev_i32_e32 v13, 31, v12
	v_lshlrev_b64 v[28:29], 11, v[12:13]
	v_and_b32_e32 v14, 0x3f8, v10
	v_lshl_add_u64 v[12:13], s[2:3], 0, v[28:29]
	v_lshlrev_b32_e32 v30, 1, v14
	v_mov_b32_e32 v31, v0
	v_lshl_add_u64 v[12:13], v[12:13], 0, v[30:31]
	global_load_dwordx4 v[12:15], v[12:13], off nt
	v_lshl_add_u64 v[16:17], s[4:5], 0, v[28:29]
	v_lshl_add_u64 v[16:17], v[16:17], 0, v[30:31]
	global_load_dwordx4 v[16:19], v[16:17], off nt
	v_add_u32_e32 v1, s76, v1
	v_add_u32_e32 v10, s92, v10
	v_ashrrev_i32_e32 v60, 7, v1
	v_ashrrev_i32_e32 v61, 31, v60
	v_lshlrev_b64 v[76:77], 11, v[60:61]
	v_and_b32_e32 v62, 0x3f8, v10
	v_lshl_add_u64 v[60:61], s[2:3], 0, v[76:77]
	v_lshlrev_b32_e32 v78, 1, v62
	v_mov_b32_e32 v79, v0
	v_lshl_add_u64 v[60:61], v[60:61], 0, v[78:79]
	global_load_dwordx4 v[60:63], v[60:61], off nt
	v_lshl_add_u64 v[64:65], s[4:5], 0, v[76:77]
	v_lshl_add_u64 v[64:65], v[64:65], 0, v[78:79]
	global_load_dwordx4 v[64:67], v[64:65], off nt
	v_add_u32_e32 v1, s76, v1
	v_add_u32_e32 v10, s92, v10
	s_waitcnt vmcnt(3)
	v_and_b32_e32 v33, 0xffff0000, v15
	v_and_b32_e32 v37, 0xffff0000, v14
	v_lshlrev_b32_e32 v32, 16, v15
	v_lshlrev_b32_e32 v36, 16, v14
	v_mov_b32_e32 v38, v33
	v_mov_b32_e32 v39, v37
	v_mov_b32_e32 v14, v32
	v_mov_b32_e32 v15, v36
	v_pk_mul_f32 v[38:39], v[38:39], v[38:39]
	s_waitcnt vmcnt(2)
	v_lshlrev_b32_e32 v34, 16, v19
	v_pk_fma_f32 v[14:15], v[14:15], v[14:15], v[38:39]
	v_lshlrev_b32_e32 v38, 16, v18
	v_and_b32_e32 v39, 0xffff0000, v18
	v_mul_f32_e32 v11, 0xbfb8aa3b, v38
	v_exp_f32_e32 v18, v11
	v_mul_f32_e32 v11, 0xbfb8aa3b, v39
	v_and_b32_e32 v35, 0xffff0000, v19
	v_exp_f32_e32 v19, v11
	s_nop 0
	v_pk_add_f32 v[18:19], v[18:19], 1.0 op_sel_hi:[1,0]
	s_nop 0
	s_nop 0
	s_nop 0
	s_nop 0
	s_nop 0
	s_nop 0
	s_nop 0
	s_nop 0
	s_nop 0
	s_nop 0
	s_nop 0
	s_nop 0
	v_rcp_f32_e32 v19, v19
	s_nop 0
	s_nop 0
	s_nop 0
	s_nop 0
	s_nop 0
	s_nop 0
	s_nop 0
	s_nop 0
	s_nop 0
	s_nop 0
	s_nop 0
	v_lshlrev_b32_e32 v40, 16, v17
	v_rcp_f32_e32 v18, v18
	v_and_b32_e32 v41, 0xffff0000, v17
	v_mul_f32_e32 v11, 0xbfb8aa3b, v40
	v_exp_f32_e32 v42, v11
	v_mul_f32_e32 v11, 0xbfb8aa3b, v41
	v_exp_f32_e32 v43, v11
	v_pk_mul_f32 v[18:19], v[18:19], v[38:39]
	v_lshlrev_b32_e32 v38, 16, v13
	v_and_b32_e32 v39, 0xffff0000, v13
	v_pk_add_f32 v[42:43], v[42:43], 1.0 op_sel_hi:[1,0]
	s_nop 0
	s_nop 0
	s_nop 0
	s_nop 0
	s_nop 0
	s_nop 0
	s_nop 0
	s_nop 0
	s_nop 0
	s_nop 0
	s_nop 0
	s_nop 0
	v_rcp_f32_e32 v43, v43
	s_nop 0
	s_nop 0
	s_nop 0
	s_nop 0
	s_nop 0
	s_nop 0
	s_nop 0
	s_nop 0
	s_nop 0
	s_nop 0
	s_nop 0
	v_rcp_f32_e32 v42, v42
	s_nop 0
	v_pk_mul_f32 v[40:41], v[42:43], v[40:41]
	v_and_b32_e32 v43, 0xffff0000, v12
	v_lshlrev_b32_e32 v42, 16, v12
	v_mov_b32_e32 v44, v43
	v_mov_b32_e32 v45, v39
	v_mov_b32_e32 v12, v42
	v_mov_b32_e32 v13, v38
	v_pk_mul_f32 v[44:45], v[44:45], v[44:45]
	s_nop 0
	v_pk_fma_f32 v[12:13], v[12:13], v[12:13], v[44:45]
	v_lshlrev_b32_e32 v44, 16, v16
	v_and_b32_e32 v45, 0xffff0000, v16
	v_mul_f32_e32 v11, 0xbfb8aa3b, v44
	v_exp_f32_e32 v16, v11
	v_mul_f32_e32 v11, 0xbfb8aa3b, v45
	v_exp_f32_e32 v17, v11
	s_nop 0
	v_pk_add_f32 v[16:17], v[16:17], 1.0 op_sel_hi:[1,0]
	s_nop 0
	s_nop 0
	s_nop 0
	s_nop 0
	s_nop 0
	s_nop 0
	s_nop 0
	s_nop 0
	s_nop 0
	s_nop 0
	s_nop 0
	s_nop 0
	v_rcp_f32_e32 v17, v17
	s_nop 0
	s_nop 0
	s_nop 0
	s_nop 0
	s_nop 0
	s_nop 0
	s_nop 0
	s_nop 0
	s_nop 0
	s_nop 0
	s_nop 0
	v_rcp_f32_e32 v16, v16
	v_add_f32_e32 v11, v12, v13
	v_add_f32_e32 v11, v15, v11
	v_add_f32_e32 v11, v14, v11
	ds_bpermute_b32 v12, v2, v11
	v_pk_mul_f32 v[16:17], v[16:17], v[44:45]
	s_waitcnt lgkmcnt(0)
	v_add_f32_e32 v11, v11, v12
	ds_bpermute_b32 v12, v3, v11
	s_waitcnt lgkmcnt(0)
	v_add_f32_e32 v11, v11, v12
	ds_bpermute_b32 v12, v8, v11
	s_waitcnt lgkmcnt(0)
	v_add_f32_e32 v11, v11, v12
	ds_bpermute_b32 v12, v9, v11
	s_waitcnt lgkmcnt(0)
	v_add_f32_e32 v11, v11, v12
	v_fmamk_f32 v11, v11, 0x3c000000, v208
	v_cmp_gt_f32_e32 vcc, s51, v11
	v_mul_f32_e32 v12, 0x4b800000, v11
	s_nop 0
	v_cndmask_b32_e32 v11, v11, v12, vcc
	v_rsq_f32_e32 v11, v11
	s_nop 0
	v_mul_f32_e32 v12, 0x45800000, v11
	v_cndmask_b32_e32 v44, v11, v12, vcc
	v_pk_mul_f32 v[12:13], v[44:45], v[42:43] op_sel_hi:[0,1]
	v_pk_mul_f32 v[12:13], v[24:25], v[12:13]
	v_mul_f32_e32 v11, 0xbfb8aa3b, v34
	v_pk_mul_f32 v[12:13], v[16:17], v[12:13]
	v_exp_f32_e32 v16, v11
	v_mul_f32_e32 v11, 0xbfb8aa3b, v35
	v_pk_mul_f32 v[14:15], v[44:45], v[38:39] op_sel_hi:[0,1]
	v_exp_f32_e32 v17, v11
	v_pk_mul_f32 v[14:15], v[26:27], v[14:15]
	v_cvt_pk_bf16_f32 v12, v12, v13
	v_pk_mul_f32 v[14:15], v[40:41], v[14:15]
	v_pk_add_f32 v[16:17], v[16:17], 1.0 op_sel_hi:[1,0]
	v_cvt_pk_bf16_f32 v13, v14, v15
	v_pk_mul_f32 v[14:15], v[44:45], v[36:37] op_sel_hi:[0,1]
	v_pk_mul_f32 v[14:15], v[20:21], v[14:15]
	s_nop 0
	v_pk_mul_f32 v[14:15], v[18:19], v[14:15]
	v_pk_mul_f32 v[18:19], v[44:45], v[32:33] op_sel_hi:[0,1]
	v_cvt_pk_bf16_f32 v14, v14, v15
	s_nop 0
	v_pk_mul_f32 v[18:19], v[22:23], v[18:19]
	s_nop 0
	s_nop 0
	s_nop 0
	s_nop 0
	s_nop 0
	s_nop 0
	s_nop 0
	s_nop 0
	v_rcp_f32_e32 v17, v17
	s_nop 0
	s_nop 0
	s_mov_b32 s10, 0x1fffff
	s_nop 0
	s_nop 0
	s_nop 0
	s_nop 0
	s_nop 0
	s_nop 0
	s_nop 0
	s_nop 0
	v_rcp_f32_e32 v16, v16
	s_nop 0
	v_pk_mul_f32 v[16:17], v[16:17], v[34:35]
	v_cmp_lt_i32_e32 vcc, s10, v1
	v_pk_mul_f32 v[16:17], v[16:17], v[18:19]
	s_or_b64 s[8:9], vcc, s[8:9]
	v_cvt_pk_bf16_f32 v15, v16, v17
	v_lshl_add_u64 v[16:17], s[6:7], 0, v[28:29]
	v_lshl_add_u64 v[16:17], v[16:17], 0, v[30:31]
	global_store_dwordx4 v[16:17], v[12:15], off nt
	s_waitcnt vmcnt(2)
	v_and_b32_e32 v81, 0xffff0000, v63
	v_and_b32_e32 v85, 0xffff0000, v62
	v_lshlrev_b32_e32 v80, 16, v63
	v_lshlrev_b32_e32 v84, 16, v62
	v_mov_b32_e32 v86, v81
	v_mov_b32_e32 v87, v85
	v_mov_b32_e32 v62, v80
	v_mov_b32_e32 v63, v84
	v_pk_mul_f32 v[86:87], v[86:87], v[86:87]
	s_waitcnt vmcnt(1)
	v_lshlrev_b32_e32 v82, 16, v67
	v_pk_fma_f32 v[62:63], v[62:63], v[62:63], v[86:87]
	v_lshlrev_b32_e32 v86, 16, v66
	v_and_b32_e32 v87, 0xffff0000, v66
	v_mul_f32_e32 v59, 0xbfb8aa3b, v86
	v_exp_f32_e32 v66, v59
	v_mul_f32_e32 v59, 0xbfb8aa3b, v87
	v_and_b32_e32 v83, 0xffff0000, v67
	v_exp_f32_e32 v67, v59
	s_nop 0
	v_pk_add_f32 v[66:67], v[66:67], 1.0 op_sel_hi:[1,0]
	s_nop 0
	s_nop 0
	s_nop 0
	s_nop 0
	s_nop 0
	s_nop 0
	s_nop 0
	s_nop 0
	s_nop 0
	s_nop 0
	s_nop 0
	s_nop 0
	v_rcp_f32_e32 v67, v67
	s_nop 0
	s_nop 0
	s_nop 0
	s_nop 0
	s_nop 0
	s_nop 0
	s_nop 0
	s_nop 0
	s_nop 0
	s_nop 0
	s_nop 0
	v_lshlrev_b32_e32 v88, 16, v65
	v_rcp_f32_e32 v66, v66
	v_and_b32_e32 v89, 0xffff0000, v65
	v_mul_f32_e32 v59, 0xbfb8aa3b, v88
	v_exp_f32_e32 v90, v59
	v_mul_f32_e32 v59, 0xbfb8aa3b, v89
	v_exp_f32_e32 v91, v59
	v_pk_mul_f32 v[66:67], v[66:67], v[86:87]
	v_lshlrev_b32_e32 v86, 16, v61
	v_and_b32_e32 v87, 0xffff0000, v61
	v_pk_add_f32 v[90:91], v[90:91], 1.0 op_sel_hi:[1,0]
	s_nop 0
	s_nop 0
	s_nop 0
	s_nop 0
	s_nop 0
	s_nop 0
	s_nop 0
	s_nop 0
	s_nop 0
	s_nop 0
	s_nop 0
	s_nop 0
	v_rcp_f32_e32 v91, v91
	s_nop 0
	s_nop 0
	s_nop 0
	s_nop 0
	s_nop 0
	s_nop 0
	s_nop 0
	s_nop 0
	s_nop 0
	s_nop 0
	s_nop 0
	v_rcp_f32_e32 v90, v90
	s_nop 0
	v_pk_mul_f32 v[88:89], v[90:91], v[88:89]
	v_and_b32_e32 v91, 0xffff0000, v60
	v_lshlrev_b32_e32 v90, 16, v60
	v_mov_b32_e32 v92, v91
	v_mov_b32_e32 v93, v87
	v_mov_b32_e32 v60, v90
	v_mov_b32_e32 v61, v86
	v_pk_mul_f32 v[92:93], v[92:93], v[92:93]
	s_nop 0
	v_pk_fma_f32 v[60:61], v[60:61], v[60:61], v[92:93]
	v_lshlrev_b32_e32 v92, 16, v64
	v_and_b32_e32 v93, 0xffff0000, v64
	v_mul_f32_e32 v59, 0xbfb8aa3b, v92
	v_exp_f32_e32 v64, v59
	v_mul_f32_e32 v59, 0xbfb8aa3b, v93
	v_exp_f32_e32 v65, v59
	s_nop 0
	v_pk_add_f32 v[64:65], v[64:65], 1.0 op_sel_hi:[1,0]
	s_nop 0
	s_nop 0
	s_nop 0
	s_nop 0
	s_nop 0
	s_nop 0
	s_nop 0
	s_nop 0
	s_nop 0
	s_nop 0
	s_nop 0
	s_nop 0
	v_rcp_f32_e32 v65, v65
	s_nop 0
	s_nop 0
	s_nop 0
	s_nop 0
	s_nop 0
	s_nop 0
	s_nop 0
	s_nop 0
	s_nop 0
	s_nop 0
	s_nop 0
	v_rcp_f32_e32 v64, v64
	v_add_f32_e32 v59, v60, v61
	v_add_f32_e32 v59, v63, v59
	v_add_f32_e32 v59, v62, v59
	ds_bpermute_b32 v60, v2, v59
	v_pk_mul_f32 v[64:65], v[64:65], v[92:93]
	s_waitcnt lgkmcnt(0)
	v_add_f32_e32 v59, v59, v60
	ds_bpermute_b32 v60, v3, v59
	s_waitcnt lgkmcnt(0)
	v_add_f32_e32 v59, v59, v60
	ds_bpermute_b32 v60, v8, v59
	s_waitcnt lgkmcnt(0)
	v_add_f32_e32 v59, v59, v60
	ds_bpermute_b32 v60, v9, v59
	s_waitcnt lgkmcnt(0)
	v_add_f32_e32 v59, v59, v60
	v_fmamk_f32 v59, v59, 0x3c000000, v208
	v_cmp_gt_f32_e32 vcc, s51, v59
	v_mul_f32_e32 v60, 0x4b800000, v59
	s_nop 0
	v_cndmask_b32_e32 v59, v59, v60, vcc
	v_rsq_f32_e32 v59, v59
	s_nop 0
	v_mul_f32_e32 v60, 0x45800000, v59
	v_cndmask_b32_e32 v92, v59, v60, vcc
	v_pk_mul_f32 v[60:61], v[92:93], v[90:91] op_sel_hi:[0,1]
	v_pk_mul_f32 v[60:61], v[24:25], v[60:61]
	v_mul_f32_e32 v59, 0xbfb8aa3b, v82
	v_pk_mul_f32 v[60:61], v[64:65], v[60:61]
	v_exp_f32_e32 v64, v59
	v_mul_f32_e32 v59, 0xbfb8aa3b, v83
	v_pk_mul_f32 v[62:63], v[92:93], v[86:87] op_sel_hi:[0,1]
	v_exp_f32_e32 v65, v59
	v_pk_mul_f32 v[62:63], v[26:27], v[62:63]
	v_cvt_pk_bf16_f32 v60, v60, v61
	v_pk_mul_f32 v[62:63], v[88:89], v[62:63]
	v_pk_add_f32 v[64:65], v[64:65], 1.0 op_sel_hi:[1,0]
	v_cvt_pk_bf16_f32 v61, v62, v63
	v_pk_mul_f32 v[62:63], v[92:93], v[84:85] op_sel_hi:[0,1]
	v_pk_mul_f32 v[62:63], v[20:21], v[62:63]
	s_nop 0
	v_pk_mul_f32 v[62:63], v[66:67], v[62:63]
	v_pk_mul_f32 v[66:67], v[92:93], v[80:81] op_sel_hi:[0,1]
	v_cvt_pk_bf16_f32 v62, v62, v63
	s_nop 0
	v_pk_mul_f32 v[66:67], v[22:23], v[66:67]
	s_nop 0
	s_nop 0
	s_nop 0
	s_nop 0
	s_nop 0
	s_nop 0
	s_nop 0
	s_nop 0
	v_rcp_f32_e32 v65, v65
	s_nop 0
	s_nop 0
	s_mov_b32 s10, 0x1fffff
	s_nop 0
	s_nop 0
	s_nop 0
	s_nop 0
	s_nop 0
	s_nop 0
	s_nop 0
	s_nop 0
	v_rcp_f32_e32 v64, v64
	s_nop 0
	v_pk_mul_f32 v[64:65], v[64:65], v[82:83]
	v_cmp_lt_i32_e32 vcc, s10, v1
	v_pk_mul_f32 v[64:65], v[64:65], v[66:67]
	s_or_b64 s[8:9], vcc, s[8:9]
	v_cvt_pk_bf16_f32 v63, v64, v65
	v_lshl_add_u64 v[64:65], s[6:7], 0, v[76:77]
	v_lshl_add_u64 v[64:65], v[64:65], 0, v[78:79]
	global_store_dwordx4 v[64:65], v[60:63], off nt
	s_andn2_b64 exec, exec, s[8:9]
	s_cbranch_execnz .LBB0_761
